# on top of the flat release poll: forgetting-attention work queue index for the next unit fetched at the end of the current unit (atomic latency hidden under the unit epilogue)
# baseline (speedup 1.0000x reference)
.LBB0_853:
	s_cmp_lt_i32 s78, 11
	s_cselect_b64 s[2:3], -1, 0
	s_and_b64 s[0:1], s[2:3], s[0:1]
	v_writelane_b32 v254, s0, 60
	s_andn2_b64 vcc, exec, s[0:1]
	s_nop 0
	v_writelane_b32 v254, s1, 61
	s_cbranch_vccnz .LBB0_910
	s_add_u32 s0, s76, 0x300000
	v_writelane_b32 v254, s0, 62
	s_addc_u32 s0, s77, 0
	v_writelane_b32 v254, s0, 63
	s_mov_b32 s1, 0
	v_writelane_b32 v254, s0, 38
	v_mbcnt_lo_u32_b32 v0, -1, 0
	s_waitcnt lgkmcnt(0)
	v_mov_b32_e32 v1, 0
	v_writelane_b32 v254, s1, 39
	v_writelane_b32 v254, s66, 4
	s_add_i32 s0, 0, 0x20840
	v_writelane_b32 v255, s0, 0
	v_writelane_b32 v254, s67, 5
	v_writelane_b32 v254, s96, 2
	v_mov_b32_e32 v188, s0
	v_mov_b32_e32 v189, 0x260
	v_mbcnt_hi_u32_b32 v191, -1, v0
	v_mov_b32_e32 v192, 0xff800000
	v_writelane_b32 v254, s97, 3
	s_mov_b32 s98, 0
	s_branch .LBB0_857

.LBB0_857:
	s_mov_b64 s[0:1], exec
	v_readlane_b32 s2, v253, 6
	v_readlane_b32 s3, v253, 7
	s_and_b64 s[2:3], s[0:1], s[2:3]
	s_mov_b64 exec, s[2:3]
	s_cbranch_execz .LBB0_861
	s_mov_b64 s[4:5], exec
	v_mbcnt_lo_u32_b32 v0, s4, 0
	v_mbcnt_hi_u32_b32 v0, s5, v0
	v_cmp_eq_u32_e32 vcc, 0, v0
	s_and_saveexec_b64 s[2:3], vcc
	s_cbranch_execz .LBB0_860
	s_cmp_lg_u32 s98, 0
	s_cbranch_scc1 .LBB0_860
	s_bcnt1_i32_b64 s4, s[4:5]
	v_mov_b32_e32 v246, s4
	global_atomic_add v246, v1, v246, s[76:77] offset:256 sc0
.LBB0_860:
	s_or_b64 exec, exec, s[2:3]
	s_waitcnt vmcnt(0)
	v_readfirstlane_b32 s2, v246
	s_nop 1
	v_add_u32_e32 v0, s2, v0
	v_readlane_b32 s2, v255, 0
	s_nop 1
	v_mov_b32_e32 v2, s2
	ds_write_b32 v2, v0

.LBB0_905:
	v_readlane_b32 s0, v253, 24
	s_and_b32 s0, s0, 0x3fffffc0
	s_setprio 0
	s_waitcnt vmcnt(0) lgkmcnt(0)
	s_barrier
	v_readlane_b32 s98, v253, 6
	v_readlane_b32 s99, v253, 7
	s_and_saveexec_b64 s[100:101], s[98:99]
	s_cbranch_execz .Lq_nopf
	v_mov_b32_e32 v246, 1
	global_atomic_add v246, v1, v246, s[76:77] offset:256 sc0
	s_mov_b32 s98, 1
.Lq_nopf:
	s_mov_b64 exec, s[100:101]
	s_lshl_b32 s0, s0, 2
	s_add_i32 s2, s0, 0
	v_and_b32_e32 v0, 63, v193
	v_mov_b32_e32 v4, v205
	v_mov_b32_e32 v3, v205
	v_and_b32_e32 v2, 31, v193
	s_add_i32 s2, s2, 0x18000
	v_permlane32_swap_b32_e32 v4, v3
	v_cmp_gt_u32_e32 vcc, 32, v0
	s_and_saveexec_b64 s[0:1], vcc
	s_cbranch_execz .LBB0_855
	v_lshl_add_u32 v4, v2, 2, s2
	v_add_f32_e32 v3, v205, v3
	ds_write_b32 v4, v3 offset:128
	s_branch .LBB0_855
